# HW wave-slot stagger extended to the custom out-proj and ffn_out double-tile GEMMs (all four custom GEMM phases)
# speedup vs baseline: 1.0072x; 1.0027x over previous
.LBB0_2100:
	v_readlane_b32 s2, v249, 52
	s_lshl_b32 s72, s2, 10
	s_lshl_b64 s[4:5], s[72:73], 10
	s_lshl_b32 s18, s14, 3
	s_cmp_ge_i32 s16, s18
	v_readlane_b32 s3, v249, 53
	s_cbranch_scc1 .LBB0_2211
	s_lshr_b32 s19, s14, 3
	s_lshl_b64 s[2:3], s[4:5], 1
	s_waitcnt lgkmcnt(0)
	s_add_u32 s20, s0, s2
	v_and_b32_e32 v2, 15, v0
	v_ashrrev_i32_e32 v3, 1, v0
	s_movk_i32 s2, 0xffc0
	s_addc_u32 s21, s1, s3
	v_and_or_b32 v80, v3, s2, v2
	v_readlane_b32 s2, v249, 52
	v_readlane_b32 s3, v249, 53
	s_cmp_lt_i32 s15, 0
	s_mov_b32 s3, s73
	s_cselect_b64 s[10:11], -1, 0
	v_lshrrev_b32_e32 v2, 2, v0
	s_mov_b32 s12, s2
	s_lshl_b64 s[2:3], s[2:3], 21
	v_and_b32_e32 v2, 12, v2
	v_writelane_b32 v249, s12, 52
	s_add_u32 s22, s0, s2
	v_and_or_b32 v81, v0, 64, v2
	v_writelane_b32 v249, s13, 53
	s_addc_u32 s23, s1, s3
	v_readlane_b32 s24, v249, 1
	s_nop 0
	s_cmpk_lg_u32 s24, 0x200
	s_cbranch_scc1 .LBB0_2104
	s_getreg_b32 s24, hwreg(HW_REG_HW_ID, 0, 4)
	s_and_b32 s24, s24, 1
	s_cmp_eq_u32 s24, 0
	s_cbranch_scc1 .Lr2u_nostag
	s_sleep 41
.Lr2u_nostag:
	s_load_dwordx2 s[38:39], s[84:85], 0x130
	s_load_dwordx2 s[48:49], s[84:85], 0x0
	v_readlane_b32 s24, v249, 0
	s_nop 0
	s_and_b32 s25, s24, 7
	s_lshr_b32 s24, s24, 3
	s_and_b32 s27, s24, 7
	s_lshr_b32 s24, s24, 3
	s_and_b32 s28, s24, 3
	s_lshr_b32 s24, s24, 2
	s_lshl_b32 s24, s24, 3
	s_add_i32 s24, s24, s28
	s_lshl_b32 s24, s24, 3
	s_add_i32 s28, s24, s25
	s_add_i32 s29, s28, 32
	s_mul_i32 s24, s28, 0x40000
	s_add_u32 s30, s8, s24
	s_addc_u32 s31, s9, 0
	s_mul_i32 s24, s29, 0x40000
	s_add_u32 s44, s8, s24
	s_addc_u32 s45, s9, 0
	s_mul_i32 s24, s27, 0x40000
	s_add_u32 s34, s22, s24
	s_addc_u32 s35, s23, 0
	s_waitcnt lgkmcnt(0)
	s_lshl_b32 s27, s27, 9
	s_lshl_b32 s24, s28, 19
	s_add_i32 s24, s24, s27
	s_add_u32 s40, s38, s24
	s_addc_u32 s41, s39, 0
	s_lshl_b32 s24, s29, 19
	s_add_i32 s24, s24, s27
	s_add_u32 s42, s38, s24
	s_addc_u32 s43, s39, 0
	v_readlane_b32 s25, v249, 52
	s_nop 0
	s_cmp_eq_u32 s25, 0
	s_cselect_b32 s48, s48, s38
	s_cselect_b32 s49, s49, s39
	s_sub_u32 s25, s40, s38
	s_add_u32 s50, s48, s25
	s_addc_u32 s51, s49, 0
	s_add_u32 s52, s48, s24
	s_addc_u32 s53, s49, 0
	v_and_b32_e32 v144, 7, v196
	v_bfe_u32 v145, v196, 4, 2
	v_bfe_u32 v146, v196, 6, 1
	v_lshl_or_b32 v147, v146, 2, v145
	v_xor_b32_e32 v144, v144, v147
	v_lshrrev_b32_e32 v147, 3, v196
	v_mul_u32_u24_e32 v147, 0x800, v147
	v_lshl_or_b32 v136, v144, 4, v147
	v_add_u32_e32 v137, 0x10000, v136
	v_add_u32_e32 v138, 0x20000, v136
	v_add_u32_e32 v139, 0x30000, v136
	v_and_b32_e32 v144, 15, v196
	v_bfe_u32 v147, v196, 1, 3
	v_xor_b32_e32 v147, v145, v147
	v_lshlrev_b32_e32 v147, 4, v147
	v_xor_b32_e32 v130, 64, v147
	v_lshlrev_b32_e32 v144, 7, v144
	v_lshrrev_b32_e32 v131, 7, v196
	v_lshl_or_b32 v131, v131, 13, v144
	v_lshl_or_b32 v133, v146, 13, v144
	v_add_u32_e32 v140, v131, v147
	v_add_u32_e32 v141, v131, v130
	v_add_u32_e32 v142, v133, v147
	v_add_u32_e32 v143, v133, v130
	v_readfirstlane_b32 s36, v196
	s_lshr_b32 s36, s36, 6
	s_lshl_b32 s36, s36, 10
	s_barrier
	s_add_i32 m0, s36, 0x0
	s_nop 0
	global_load_lds_dwordx4 v136, s[30:31]
	s_add_i32 m0, s36, 0x1000
	s_nop 0
	global_load_lds_dwordx4 v137, s[30:31]
	s_add_i32 m0, s36, 0x2000
	s_nop 0
	global_load_lds_dwordx4 v138, s[30:31]
	s_add_i32 m0, s36, 0x3000
	s_nop 0
	global_load_lds_dwordx4 v139, s[30:31]
	s_add_i32 m0, s36, 0x4000
	s_nop 0
	global_load_lds_dwordx4 v136, s[44:45]
	s_add_i32 m0, s36, 0x5000
	s_nop 0
	global_load_lds_dwordx4 v137, s[44:45]
	s_add_i32 m0, s36, 0x6000
	s_nop 0
	global_load_lds_dwordx4 v138, s[44:45]
	s_add_i32 m0, s36, 0x7000
	s_nop 0
	global_load_lds_dwordx4 v139, s[44:45]
	s_add_u32 s30, s30, 0x80
	s_addc_u32 s31, s31, 0
	s_add_u32 s44, s44, 0x80
	s_addc_u32 s45, s45, 0
	s_add_i32 m0, s36, 0x8000
	s_nop 0
	global_load_lds_dwordx4 v136, s[34:35]
	s_add_i32 m0, s36, 0x9000
	s_nop 0
	global_load_lds_dwordx4 v137, s[34:35]
	s_add_i32 m0, s36, 0xa000
	s_nop 0
	global_load_lds_dwordx4 v138, s[34:35]
	s_add_i32 m0, s36, 0xb000
	s_nop 0
	global_load_lds_dwordx4 v139, s[34:35]
	s_add_u32 s34, s34, 0x80
	s_addc_u32 s35, s35, 0
	v_mov_b64_e32 v[62:63], 0
	v_mov_b64_e32 v[64:65], 0
	v_mov_b64_e32 v[58:59], 0
	v_mov_b64_e32 v[60:61], 0
	v_mov_b64_e32 v[54:55], 0
	v_mov_b64_e32 v[56:57], 0
	v_mov_b64_e32 v[50:51], 0
	v_mov_b64_e32 v[52:53], 0
	v_mov_b64_e32 v[46:47], 0
	v_mov_b64_e32 v[48:49], 0
	v_mov_b64_e32 v[42:43], 0
	v_mov_b64_e32 v[44:45], 0
	v_mov_b64_e32 v[38:39], 0
	v_mov_b64_e32 v[40:41], 0
	v_mov_b64_e32 v[34:35], 0
	v_mov_b64_e32 v[36:37], 0
	v_mov_b64_e32 v[30:31], 0
	v_mov_b64_e32 v[32:33], 0
	v_mov_b64_e32 v[26:27], 0
	v_mov_b64_e32 v[28:29], 0
	v_mov_b64_e32 v[22:23], 0
	v_mov_b64_e32 v[24:25], 0
	v_mov_b64_e32 v[18:19], 0
	v_mov_b64_e32 v[20:21], 0
	v_mov_b64_e32 v[14:15], 0
	v_mov_b64_e32 v[16:17], 0
	v_mov_b64_e32 v[10:11], 0
	v_mov_b64_e32 v[12:13], 0
	v_mov_b64_e32 v[6:7], 0
	v_mov_b64_e32 v[8:9], 0
	v_mov_b64_e32 v[2:3], 0
	v_mov_b64_e32 v[4:5], 0
	v_mov_b64_e32 v[66:67], 0
	v_mov_b64_e32 v[68:69], 0
	v_mov_b64_e32 v[70:71], 0
	v_mov_b64_e32 v[72:73], 0
	v_mov_b64_e32 v[74:75], 0
	v_mov_b64_e32 v[76:77], 0
	v_mov_b64_e32 v[78:79], 0
	v_mov_b64_e32 v[80:81], 0
	v_mov_b64_e32 v[82:83], 0
	v_mov_b64_e32 v[84:85], 0
	v_mov_b64_e32 v[86:87], 0
	v_mov_b64_e32 v[88:89], 0
	v_mov_b64_e32 v[90:91], 0
	v_mov_b64_e32 v[92:93], 0
	v_mov_b64_e32 v[94:95], 0
	v_mov_b64_e32 v[96:97], 0
	v_mov_b64_e32 v[98:99], 0
	v_mov_b64_e32 v[100:101], 0
	v_mov_b64_e32 v[102:103], 0
	v_mov_b64_e32 v[104:105], 0
	v_mov_b64_e32 v[106:107], 0
	v_mov_b64_e32 v[108:109], 0
	v_mov_b64_e32 v[110:111], 0
	v_mov_b64_e32 v[112:113], 0
	v_mov_b64_e32 v[114:115], 0
	v_mov_b64_e32 v[116:117], 0
	v_mov_b64_e32 v[118:119], 0
	v_mov_b64_e32 v[120:121], 0
	v_mov_b64_e32 v[122:123], 0
	v_mov_b64_e32 v[124:125], 0
	v_mov_b64_e32 v[126:127], 0
	v_mov_b64_e32 v[128:129], 0
	s_movk_i32 s37, 7

.LBB0_2414:
	s_lshl_b32 s16, s12, 3
	v_readlane_b32 s6, v249, 52
	s_mul_i32 s0, s72, 0xb00
	s_mov_b32 s1, s73
	s_cmp_ge_i32 s14, s16
	s_mul_hi_u32 s10, s6, 0x580000
	s_mul_i32 s11, s6, 0x580000
	v_readlane_b32 s7, v249, 53
	s_cbranch_scc1 .LBB0_2422
	s_lshr_b32 s17, s12, 3
	s_lshl_b64 s[6:7], s[0:1], 1
	s_waitcnt lgkmcnt(0)
	s_add_u32 s18, s8, s6
	s_addc_u32 s19, s9, s7
	v_and_b32_e32 v2, 15, v0
	v_ashrrev_i32_e32 v3, 1, v0
	s_movk_i32 s20, 0xffc0
	s_cmp_lt_i32 s13, 0
	v_and_or_b32 v74, v3, s20, v2
	v_lshrrev_b32_e32 v2, 2, v0
	s_cselect_b64 s[6:7], -1, 0
	v_and_b32_e32 v2, 12, v2
	s_add_u32 s20, s8, s11
	v_and_or_b32 v75, v0, 64, v2
	s_addc_u32 s21, s9, s10
	v_readlane_b32 s24, v249, 1
	s_nop 0
	s_cmpk_lg_u32 s24, 0x200
	s_cbranch_scc1 .LBB0_2417
	s_getreg_b32 s24, hwreg(HW_REG_HW_ID, 0, 4)
	s_and_b32 s24, s24, 1
	s_cmp_eq_u32 s24, 0
	s_cbranch_scc1 .Lr2o_nostag
	s_sleep 41
.Lr2o_nostag:
	s_load_dwordx2 s[38:39], s[84:85], 0x130
	v_readlane_b32 s24, v249, 0
	s_nop 0
	s_and_b32 s25, s24, 7
	s_lshr_b32 s24, s24, 3
	s_and_b32 s27, s24, 7
	s_lshr_b32 s24, s24, 3
	s_and_b32 s28, s24, 3
	s_lshr_b32 s24, s24, 2
	s_lshl_b32 s24, s24, 3
	s_add_i32 s24, s24, s28
	s_lshl_b32 s24, s24, 3
	s_add_i32 s28, s24, s25
	s_add_i32 s29, s28, 32
	s_mul_i32 s24, s28, 0xb0000
	s_add_u32 s30, s4, s24
	s_addc_u32 s31, s5, 0
	s_mul_i32 s24, s29, 0xb0000
	s_add_u32 s44, s4, s24
	s_addc_u32 s45, s5, 0
	s_mul_i32 s24, s27, 0xb0000
	s_add_u32 s34, s20, s24
	s_addc_u32 s35, s21, 0
	s_waitcnt lgkmcnt(0)
	s_lshl_b32 s27, s27, 9
	s_lshl_b32 s24, s28, 19
	s_add_i32 s24, s24, s27
	s_add_u32 s40, s38, s24
	s_addc_u32 s41, s39, 0
	s_lshl_b32 s24, s29, 19
	s_add_i32 s24, s24, s27
	s_add_u32 s42, s38, s24
	s_addc_u32 s43, s39, 0
	v_and_b32_e32 v144, 7, v196
	v_bfe_u32 v145, v196, 4, 2
	v_bfe_u32 v146, v196, 6, 1
	v_lshl_or_b32 v147, v146, 2, v145
	v_xor_b32_e32 v144, v144, v147
	v_lshrrev_b32_e32 v147, 3, v196
	v_mul_u32_u24_e32 v147, 0x1600, v147
	v_lshl_or_b32 v136, v144, 4, v147
	v_add_u32_e32 v137, 0x2c000, v136
	v_add_u32_e32 v138, 0x58000, v136
	v_add_u32_e32 v139, 0x84000, v136
	v_and_b32_e32 v144, 15, v196
	v_bfe_u32 v147, v196, 1, 3
	v_xor_b32_e32 v147, v145, v147
	v_lshlrev_b32_e32 v147, 4, v147
	v_xor_b32_e32 v130, 64, v147
	v_lshlrev_b32_e32 v144, 7, v144
	v_lshrrev_b32_e32 v131, 7, v196
	v_lshl_or_b32 v131, v131, 13, v144
	v_lshl_or_b32 v133, v146, 13, v144
	v_add_u32_e32 v140, v131, v147
	v_add_u32_e32 v141, v131, v130
	v_add_u32_e32 v142, v133, v147
	v_add_u32_e32 v143, v133, v130
	v_readfirstlane_b32 s36, v196
	s_lshr_b32 s36, s36, 6
	s_lshl_b32 s36, s36, 10
	s_barrier
	s_add_i32 m0, s36, 0x0
	s_nop 0
	global_load_lds_dwordx4 v136, s[30:31]
	s_add_i32 m0, s36, 0x1000
	s_nop 0
	global_load_lds_dwordx4 v137, s[30:31]
	s_add_i32 m0, s36, 0x2000
	s_nop 0
	global_load_lds_dwordx4 v138, s[30:31]
	s_add_i32 m0, s36, 0x3000
	s_nop 0
	global_load_lds_dwordx4 v139, s[30:31]
	s_add_i32 m0, s36, 0x4000
	s_nop 0
	global_load_lds_dwordx4 v136, s[44:45]
	s_add_i32 m0, s36, 0x5000
	s_nop 0
	global_load_lds_dwordx4 v137, s[44:45]
	s_add_i32 m0, s36, 0x6000
	s_nop 0
	global_load_lds_dwordx4 v138, s[44:45]
	s_add_i32 m0, s36, 0x7000
	s_nop 0
	global_load_lds_dwordx4 v139, s[44:45]
	s_add_u32 s30, s30, 0x80
	s_addc_u32 s31, s31, 0
	s_add_u32 s44, s44, 0x80
	s_addc_u32 s45, s45, 0
	s_add_i32 m0, s36, 0x8000
	s_nop 0
	global_load_lds_dwordx4 v136, s[34:35]
	s_add_i32 m0, s36, 0x9000
	s_nop 0
	global_load_lds_dwordx4 v137, s[34:35]
	s_add_i32 m0, s36, 0xa000
	s_nop 0
	global_load_lds_dwordx4 v138, s[34:35]
	s_add_i32 m0, s36, 0xb000
	s_nop 0
	global_load_lds_dwordx4 v139, s[34:35]
	s_add_u32 s34, s34, 0x80
	s_addc_u32 s35, s35, 0
	v_mov_b64_e32 v[62:63], 0
	v_mov_b64_e32 v[64:65], 0
	v_mov_b64_e32 v[58:59], 0
	v_mov_b64_e32 v[60:61], 0
	v_mov_b64_e32 v[54:55], 0
	v_mov_b64_e32 v[56:57], 0
	v_mov_b64_e32 v[50:51], 0
	v_mov_b64_e32 v[52:53], 0
	v_mov_b64_e32 v[46:47], 0
	v_mov_b64_e32 v[48:49], 0
	v_mov_b64_e32 v[42:43], 0
	v_mov_b64_e32 v[44:45], 0
	v_mov_b64_e32 v[38:39], 0
	v_mov_b64_e32 v[40:41], 0
	v_mov_b64_e32 v[34:35], 0
	v_mov_b64_e32 v[36:37], 0
	v_mov_b64_e32 v[30:31], 0
	v_mov_b64_e32 v[32:33], 0
	v_mov_b64_e32 v[26:27], 0
	v_mov_b64_e32 v[28:29], 0
	v_mov_b64_e32 v[22:23], 0
	v_mov_b64_e32 v[24:25], 0
	v_mov_b64_e32 v[18:19], 0
	v_mov_b64_e32 v[20:21], 0
	v_mov_b64_e32 v[14:15], 0
	v_mov_b64_e32 v[16:17], 0
	v_mov_b64_e32 v[10:11], 0
	v_mov_b64_e32 v[12:13], 0
	v_mov_b64_e32 v[6:7], 0
	v_mov_b64_e32 v[8:9], 0
	v_mov_b64_e32 v[2:3], 0
	v_mov_b64_e32 v[4:5], 0
	v_mov_b64_e32 v[66:67], 0
	v_mov_b64_e32 v[68:69], 0
	v_mov_b64_e32 v[70:71], 0
	v_mov_b64_e32 v[72:73], 0
	v_mov_b64_e32 v[74:75], 0
	v_mov_b64_e32 v[76:77], 0
	v_mov_b64_e32 v[78:79], 0
	v_mov_b64_e32 v[80:81], 0
	v_mov_b64_e32 v[82:83], 0
	v_mov_b64_e32 v[84:85], 0
	v_mov_b64_e32 v[86:87], 0
	v_mov_b64_e32 v[88:89], 0
	v_mov_b64_e32 v[90:91], 0
	v_mov_b64_e32 v[92:93], 0
	v_mov_b64_e32 v[94:95], 0
	v_mov_b64_e32 v[96:97], 0
	v_mov_b64_e32 v[98:99], 0
	v_mov_b64_e32 v[100:101], 0
	v_mov_b64_e32 v[102:103], 0
	v_mov_b64_e32 v[104:105], 0
	v_mov_b64_e32 v[106:107], 0
	v_mov_b64_e32 v[108:109], 0
	v_mov_b64_e32 v[110:111], 0
	v_mov_b64_e32 v[112:113], 0
	v_mov_b64_e32 v[114:115], 0
	v_mov_b64_e32 v[116:117], 0
	v_mov_b64_e32 v[118:119], 0
	v_mov_b64_e32 v[120:121], 0
	v_mov_b64_e32 v[122:123], 0
	v_mov_b64_e32 v[124:125], 0
	v_mov_b64_e32 v[126:127], 0
	v_mov_b64_e32 v[128:129], 0
	s_movk_i32 s37, 21
